# v71 + epilogue load balancing: P6 column group 0 halves swapped (silu vs natural tiles), P2 tile-row bits remapped so every workgroup has one f32-copy k/v tile
# speedup vs baseline: 1.0059x; 1.0059x over previous
;     DI bool next(int i, pg8::Unit& u) const { const int L = i * G + c; if (L >= 256) return false; u.pm = L; u.pn = 0; return true; }
;     DI bool next(int i, Unit& u) const {
;         const long L = (long)i * G + c; if (L >= nwg) return false;
;         int wgid = (int)L; { const int q = nwg / NXCD, r = nwg % NXCD, xcd = wgid % NXCD, off = wgid / NXCD; wgid = (xcd < r ? xcd * (q + 1) : r * (q + 1) + (xcd - r) * q) + off; }
;         const int nig = WGM * nN, gid = wgid / nig, fm = gid * WGM, gsz = (nM - fm) < WGM ? (nM - fm) : WGM;
;         u.pm = fm + ((wgid % nig) % gsz); u.pn = (wgid % nig) / gsz; return true;
.LBB0_165:
	s_ashr_i32 s0, s3, 3
	s_add_i32 s0, s7, s0
	s_ashr_i32 s1, s0, 31
	s_lshr_b32 s1, s1, 25
	s_add_i32 s1, s0, s1
	s_ashr_i32 s3, s1, 7
	s_and_b32 s1, s1, 0xffffff80
	s_sub_i32 s0, s0, s1
	s_bfe_i32 s1, s0, 0x80000
	s_bfe_u32 s1, s1, 0x2000d
	s_add_i32 s1, s0, s1
	s_bfe_i32 s6, s1, 0x80000
	s_and_b32 s1, s1, 0xfc
	s_sub_i32 s0, s0, s1
	s_lshl_b32 s3, s3, 2
	s_sext_i32_i16 s6, s6
	s_sext_i32_i8 s0, s0
	s_add_i32 s48, s3, s0
	s_ashr_i32 s44, s6, 2
	s_lshr_b32 s0, s48, 2
	s_and_b32 s0, s0, 3
	s_lshr_b32 s1, s0, 1
	s_xor_b32 s0, s0, s1
	s_and_b32 s0, s0, 1
	s_lshl_b32 s0, s0, 1
	s_or_b32 s0, s0, s1
	s_lshl_b32 s0, s0, 2
	s_andn2_b32 s48, s48, 12
	s_or_b32 s48, s48, s0

;     DI bool next(int i, pg8::Unit& u) const { const int L = i * G + c; if (L >= 256) return false; u.pm = L; u.pn = 0; return true; }
;     DI bool next(int i, Unit& u) const {
;         const long L = (long)i * G + c; if (L >= nwg) return false;
;         int wgid = (int)L; { const int q = nwg / NXCD, r = nwg % NXCD, xcd = wgid % NXCD, off = wgid / NXCD; wgid = (xcd < r ? xcd * (q + 1) : r * (q + 1) + (xcd - r) * q) + off; }
;         const int nig = WGM * nN, gid = wgid / nig, fm = gid * WGM, gsz = (nM - fm) < WGM ? (nM - fm) : WGM;
;         u.pm = fm + ((wgid % nig) % gsz); u.pn = (wgid % nig) / gsz; return true;
.LBB0_177:
	s_ashr_i32 s18, s34, 3
	s_add_i32 s18, s40, s18
	s_ashr_i32 s19, s18, 31
	s_lshr_b32 s19, s19, 25
	s_add_i32 s19, s18, s19
	s_ashr_i32 s34, s19, 7
	s_lshl_b32 s34, s34, 2
	s_sub_i32 s35, 64, s34
	s_min_i32 s35, s35, 4
	s_abs_i32 s40, s35
	v_cvt_f32_u32_e32 v0, s40
	s_sub_i32 s42, 0, s40
	s_and_b32 s19, s19, 0xffffff80
	s_sub_i32 s19, s18, s19
	v_rcp_iflag_f32_e32 v0, v0
	s_abs_i32 s18, s19
	s_xor_b32 s41, s19, s35
	s_ashr_i32 s41, s41, 31
	v_mul_f32_e32 v0, 0x4f7ffffe, v0
	v_cvt_u32_f32_e32 v0, v0
	s_nop 0
	v_readfirstlane_b32 s43, v0
	s_mul_i32 s42, s42, s43
	s_mul_hi_u32 s42, s43, s42
	s_add_i32 s43, s43, s42
	s_mul_hi_u32 s42, s18, s43
	s_mul_i32 s43, s42, s40
	s_sub_i32 s18, s18, s43
	s_add_i32 s45, s42, 1
	s_sub_i32 s43, s18, s40
	s_cmp_ge_u32 s18, s40
	s_cselect_b32 s42, s45, s42
	s_cselect_b32 s18, s43, s18
	s_add_i32 s43, s42, 1
	s_cmp_ge_u32 s18, s40
	s_cselect_b32 s18, s43, s42
	s_xor_b32 s18, s18, s41
	s_sub_i32 s18, s18, s41
	s_mul_i32 s35, s18, s35
	s_sub_i32 s19, s19, s35
	s_add_i32 s34, s34, s19
	s_lshr_b32 s19, s34, 2
	s_and_b32 s19, s19, 3
	s_lshr_b32 s35, s19, 1
	s_xor_b32 s19, s19, s35
	s_and_b32 s19, s19, 1
	s_lshl_b32 s19, s19, 1
	s_or_b32 s19, s19, s35
	s_lshl_b32 s19, s19, 2
	s_andn2_b32 s34, s34, 12
	s_or_b32 s34, s34, s19

;     DI bool next(int i, pg8::Unit& u) const { const int L = i * G + c; if (L >= 256) return false; u.pm = L; u.pn = 0; return true; }
;     DI bool next(int i, Unit& u) const {
;         const long L = (long)i * G + c; if (L >= nwg) return false;
;         int wgid = (int)L; { const int q = nwg / NXCD, r = nwg % NXCD, xcd = wgid % NXCD, off = wgid / NXCD; wgid = (xcd < r ? xcd * (q + 1) : r * (q + 1) + (xcd - r) * q) + off; }
;         const int nig = WGM * nN, gid = wgid / nig, fm = gid * WGM, gsz = (nM - fm) < WGM ? (nM - fm) : WGM;
;         u.pm = fm + ((wgid % nig) % gsz); u.pn = (wgid % nig) / gsz; return true;
.LBB0_898:
	v_mov_b32_e32 v8, v226
	s_cmpk_lt_i32 s2, 0x600
	s_cselect_b64 s[6:7], -1, 0
	s_cmpk_gt_i32 s2, 0x5ff
	v_readfirstlane_b32 s8, v8
	s_cbranch_scc1 .LBB0_900
	s_ashr_i32 s0, s2, 31
	s_lshr_b32 s0, s0, 29
	s_add_i32 s0, s2, s0
	s_ashr_i32 s1, s0, 3
	s_and_b32 s0, s0, -8
	s_sub_i32 s0, s2, s0
	s_cmp_lt_i32 s0, 0
	s_movk_i32 s3, 0xc1
	s_cselect_b32 s3, s3, 0xc0
	s_mul_i32 s0, s3, s0
	s_add_i32 s0, s0, s1
	s_mul_hi_i32 s1, s0, 0x2aaaaaab
	s_lshr_b32 s3, s1, 31
	s_ashr_i32 s1, s1, 4
	s_add_i32 s1, s1, s3
	s_lshl_b32 s3, s1, 2
	s_mulk_i32 s1, 0x60
	s_sub_i32 s0, s0, s1
	s_bfe_i32 s1, s0, 0x80000
	s_bfe_u32 s1, s1, 0x2000d
	s_add_i32 s1, s0, s1
	s_bfe_i32 s9, s1, 0x80000
	s_and_b32 s1, s1, 0xfc
	s_sub_i32 s0, s0, s1
	s_sext_i32_i16 s9, s9
	s_sext_i32_i8 s0, s0
	s_add_i32 s14, s3, s0
	s_ashr_i32 s12, s9, 2
	s_lshr_b32 s0, s12, 3
	s_cmp_eq_u32 s0, 0
	s_cselect_b32 s0, 4, 0
	s_xor_b32 s12, s12, s0

;     DI bool next(int i, pg8::Unit& u) const { const int L = i * G + c; if (L >= 256) return false; u.pm = L; u.pn = 0; return true; }
;     DI bool next(int i, Unit& u) const {
;         const long L = (long)i * G + c; if (L >= nwg) return false;
;         int wgid = (int)L; { const int q = nwg / NXCD, r = nwg % NXCD, xcd = wgid % NXCD, off = wgid / NXCD; wgid = (xcd < r ? xcd * (q + 1) : r * (q + 1) + (xcd - r) * q) + off; }
;         const int nig = WGM * nN, gid = wgid / nig, fm = gid * WGM, gsz = (nM - fm) < WGM ? (nM - fm) : WGM;
;         u.pm = fm + ((wgid % nig) % gsz); u.pn = (wgid % nig) / gsz; return true;
.LBB0_906:
	s_add_i32 s79, s79, 1
	s_mul_i32 s10, s79, s92
	s_mul_hi_u32 s11, s79, s93
	s_add_i32 s11, s11, s10
	s_mul_i32 s10, s79, s93
	s_add_u32 s64, s10, s2
	s_addc_u32 s65, s11, s94
	v_cmp_gt_i64_e32 vcc, s[64:65], v[152:153]
	v_cmp_lt_i64_e64 s[10:11], s[64:65], v[150:151]
	s_cbranch_vccnz .LBB0_908
	s_ashr_i32 s13, s64, 31
	s_lshr_b32 s13, s13, 29
	s_add_i32 s13, s64, s13
	s_ashr_i32 s15, s13, 3
	s_and_b32 s13, s13, -8
	s_sub_i32 s13, s64, s13
	s_cmp_lt_i32 s13, 0
	s_movk_i32 s60, 0xc1
	s_cselect_b32 s60, s60, 0xc0
	s_mul_i32 s13, s60, s13
	s_add_i32 s13, s13, s15
	s_mul_hi_i32 s15, s13, 0x2aaaaaab
	s_lshr_b32 s60, s15, 31
	s_ashr_i32 s15, s15, 4
	s_add_i32 s15, s15, s60
	s_lshl_b32 s61, s15, 2
	s_sub_i32 s60, 64, s61
	s_min_i32 s62, s60, 4
	s_abs_i32 s60, s62
	v_cvt_f32_u32_e32 v0, s60
	s_sub_i32 s64, 0, s60
	s_mulk_i32 s15, 0x60
	s_sub_i32 s13, s13, s15
	v_rcp_iflag_f32_e32 v0, v0
	s_abs_i32 s15, s13
	s_xor_b32 s63, s13, s62
	s_ashr_i32 s63, s63, 31
	v_mul_f32_e32 v0, 0x4f7ffffe, v0
	v_cvt_u32_f32_e32 v0, v0
	s_nop 0
	v_readfirstlane_b32 s65, v0
	s_mul_i32 s64, s64, s65
	s_mul_hi_u32 s64, s65, s64
	s_add_i32 s65, s65, s64
	s_mul_hi_u32 s64, s15, s65
	s_mul_i32 s65, s64, s60
	s_sub_i32 s15, s15, s65
	s_add_i32 s66, s64, 1
	s_sub_i32 s65, s15, s60
	s_cmp_ge_u32 s15, s60
	s_cselect_b32 s64, s66, s64
	s_cselect_b32 s15, s65, s15
	s_add_i32 s65, s64, 1
	s_cmp_ge_u32 s15, s60
	s_cselect_b32 s15, s65, s64
	s_xor_b32 s15, s15, s63
	s_sub_i32 s60, s15, s63
	s_mul_i32 s15, s60, s62
	s_sub_i32 s13, s13, s15
	s_add_i32 s62, s13, s61
	s_lshr_b32 s13, s60, 3
	s_cmp_eq_u32 s13, 0
	s_cselect_b32 s13, 4, 0
	s_xor_b32 s60, s60, s13
